# grid barrier: XCD leader issues its L2 invalidate right after its write-back/top-level arrive instead of after the generation flip
# baseline (speedup 1.0000x reference)
; __device__ __forceinline__ unsigned xb_ld(unsigned* p) { return __hip_atomic_load(p, __ATOMIC_RELAXED, __HIP_MEMORY_SCOPE_AGENT); }
; __device__ __forceinline__ unsigned xb_add(unsigned* p, unsigned v) { return __hip_atomic_fetch_add(p, v, __ATOMIC_RELAXED, __HIP_MEMORY_SCOPE_AGENT); }
; #define XB_SPIN(cond, bar) do { unsigned _sp = 0; while (cond) { __builtin_amdgcn_s_sleep(1); \
;     if ((++_sp & 255u) == 0u) { if (xb_ld(&(bar)[XB_TMO])) break; if (_sp > XB_SPIN_CAP) { atomicAdd(&(bar)[XB_TMO], 1u); break; } } } } while (0)
; __device__ __forceinline__ void xcd_barrier(const XcdBarrier& b) {
;     ...
;       __builtin_amdgcn_fence(__ATOMIC_RELEASE, "agent");
;       asm volatile("s_waitcnt vmcnt(0)" ::: "memory");
;       const unsigned og = xb_add(&bar[XB_TOP], 1u);
;       const unsigned tg = og / nx;
;       if (og + 1u == (tg + 1u) * nx) xb_add(&bar[XB_TOPGEN], 1u);
;       else XB_SPIN(xb_ld(&bar[XB_TOPGEN]) == tg, bar);
;       __builtin_amdgcn_fence(__ATOMIC_ACQUIRE, "agent");
.LBB0_1362:
	s_or_b64 exec, exec, s[4:5]
	buffer_inv sc1
	s_waitcnt vmcnt(0)
	v_readfirstlane_b32 s2, v2
	v_cvt_f32_u32_e32 v2, v0
	v_sub_u32_e32 v3, 0, v0
	v_add_u32_e32 v1, s2, v1
	v_readlane_b32 s0, v253, 43
	v_rcp_iflag_f32_e32 v2, v2
	v_readlane_b32 s1, v253, 44
	s_mov_b64 s[4:5], -1
	v_mul_f32_e32 v2, 0x4f7ffffe, v2
	v_cvt_u32_f32_e32 v2, v2
	v_mul_lo_u32 v3, v3, v2
	v_mul_hi_u32 v3, v2, v3
	v_add_u32_e32 v2, v2, v3
	v_mul_hi_u32 v2, v1, v2
	v_mul_lo_u32 v3, v2, v0
	v_sub_u32_e32 v3, v1, v3
	v_cmp_ge_u32_e32 vcc, v3, v0
	v_add_u32_e32 v4, 1, v2
	v_add_u32_e32 v1, 1, v1
	v_cndmask_b32_e32 v2, v2, v4, vcc
	v_sub_u32_e32 v4, v3, v0
	v_cndmask_b32_e32 v3, v3, v4, vcc
	v_cmp_ge_u32_e32 vcc, v3, v0
	v_add_u32_e32 v3, 1, v2
	s_nop 0
	v_cndmask_b32_e32 v2, v2, v3, vcc
	v_mul_lo_u32 v3, v0, v2
	v_add_u32_e32 v0, v3, v0
	v_cmp_ne_u32_e32 vcc, v1, v0
	v_mov_b64_e32 v[0:1], s[0:1]
	s_and_saveexec_b64 s[2:3], vcc
	s_cbranch_execz .LBB0_1374
	v_readlane_b32 s0, v253, 43
	v_readlane_b32 s1, v253, 44
	s_mov_b64 s[12:13], 0
	s_nop 3
	global_load_dword v0, v149, s[0:1] sc1
	s_waitcnt vmcnt(0)
	v_cmp_eq_u32_e32 vcc, v0, v2
	s_and_saveexec_b64 s[4:5], vcc
	s_cbranch_execz .LBB0_1373
	s_mov_b32 s10, 1
	s_branch .LBB0_1366

; __device__ __forceinline__ unsigned xb_add(unsigned* p, unsigned v) { return __hip_atomic_fetch_add(p, v, __ATOMIC_RELAXED, __HIP_MEMORY_SCOPE_AGENT); }
; __device__ __forceinline__ void xcd_barrier(const XcdBarrier& b) {
;     ...
;       __builtin_amdgcn_fence(__ATOMIC_ACQUIRE, "agent");
;       xb_add(&bar[XB_XGEN(b.x)], 1u);
.LBB0_1376:
	s_or_b64 exec, exec, s[2:3]
	s_mov_b64 s[2:3], exec
	v_mbcnt_lo_u32_b32 v0, s2, 0
	v_mbcnt_hi_u32_b32 v0, s3, v0
	v_cmp_eq_u32_e32 vcc, 0, v0
	s_waitcnt vmcnt(0)
	s_and_saveexec_b64 s[4:5], vcc
	s_cbranch_execnz .LBB0_1377
	s_getpc_b64 s[98:99]
